# single-hop release also in the split barriers 4 and 5: non-leader workgroups poll the top-level generation word
# speedup vs baseline: 1.0156x; 1.0112x over previous
; #define LAS __attribute__((address_space(3)))
; DI bf16_t f2bf(float a) { return (bf16_t)(pk2(a, 0.f) & 0xffffu); }
; DI float bf2f(bf16_t v) { return __uint_as_float(((unsigned)v) << 16); }
; template <bool SAMPLE>
; DI void gla_out(const Params& p, int item, int tbsel, LAS unsigned char* wl, int lane) {
;     ...
;     for (int hf = 0; hf < nhalf; ++hf) {
;         float lav[HB]; bf16_t qvv[HB], kvv[HB];
; #pragma unroll
;         for (int t = 0; t < HB; ++t) { lav[t] = la[(hf * 32 + t) * 256]; qvv[t] = qb[(hf * 32 + t) * 256]; kvv[t] = kb[(hf * 32 + t) * 256]; }
; #pragma unroll
;         for (int t = 0; t < HB; ++t) {
;             cum += lav[t];
;             const float qv = bf2f(qvv[t]) * __expf(cum), kv = bf2f(kvv[t]) * __expf(-cum);
;             *(LAS bf16_t*)(Qs + (hf * 32 + t) * 144 + 2 * lane) = f2bf(qv);
;             *(LAS bf16_t*)(Ks + (hf * 32 + t) * 144 + 2 * lane) = f2bf(kv);
;         }
;     }
.LBB0_1132:
	v_lshl_add_u64 v[4:5], s[42:43], 0, v[2:3]
	v_add_co_u32_e64 v12, s[40:41], s62, v4
	v_lshl_add_u64 v[6:7], s[42:43], 0, v[0:1]
	s_nop 0
	v_addc_co_u32_e64 v13, s[40:41], 0, v5, s[40:41]
	v_add_co_u32_e64 v14, s[40:41], s64, v4
	v_add_co_u32_e32 v10, vcc, 0xb950000, v6
	s_nop 0
	v_addc_co_u32_e64 v15, s[40:41], 0, v5, s[40:41]
	v_add_co_u32_e64 v16, s[40:41], s63, v4
	v_addc_co_u32_e32 v11, vcc, 0, v7, vcc
	s_nop 0
	v_addc_co_u32_e64 v17, s[40:41], 0, v5, s[40:41]
	v_add_co_u32_e64 v18, s[40:41], s65, v4
	v_add_co_u32_e32 v24, vcc, 0xb951000, v6
	s_nop 0
	v_addc_co_u32_e64 v19, s[40:41], 0, v5, s[40:41]
	v_add_co_u32_e64 v20, s[40:41], s66, v4
	v_addc_co_u32_e32 v25, vcc, 0, v7, vcc
	s_nop 0
	v_addc_co_u32_e64 v21, s[40:41], 0, v5, s[40:41]
	v_add_co_u32_e64 v22, s[40:41], s67, v4
	s_add_i32 s39, s39, -1
	s_nop 0
	v_addc_co_u32_e64 v23, s[40:41], 0, v5, s[40:41]
	global_load_ushort v26, v[12:13], off offset:512
	global_load_ushort v27, v[16:17], off offset:512
	global_load_ushort v28, v[12:13], off offset:1024
	global_load_ushort v29, v[12:13], off offset:1536
	global_load_ushort v30, v[12:13], off offset:2048
	global_load_ushort v31, v[12:13], off offset:2560
	global_load_ushort v32, v[12:13], off offset:3072
	global_load_ushort v33, v[12:13], off offset:3584
	global_load_ushort v34, v[18:19], off offset:-4096
	global_load_ushort v35, v[14:15], off offset:512
	global_load_ushort v36, v[14:15], off offset:1024
	global_load_ushort v37, v[14:15], off offset:1536
	global_load_ushort v38, v[14:15], off offset:2048
	global_load_ushort v39, v[14:15], off offset:2560
	global_load_ushort v40, v[14:15], off offset:3072
	global_load_ushort v41, v[14:15], off offset:3584
	global_load_ushort v42, v[18:19], off
	global_load_ushort v43, v[18:19], off offset:512
	global_load_ushort v44, v[18:19], off offset:1024
	global_load_ushort v45, v[18:19], off offset:1536
	global_load_ushort v46, v[18:19], off offset:2048
	global_load_ushort v47, v[18:19], off offset:2560
	global_load_ushort v48, v[18:19], off offset:3072
	s_nop 0
	global_load_ushort v18, v[18:19], off offset:3584
	s_nop 0
	global_load_ushort v19, v[16:17], off offset:1024
	global_load_ushort v49, v[16:17], off offset:1536
	global_load_ushort v50, v[16:17], off offset:2048
	global_load_ushort v51, v[16:17], off offset:2560
	global_load_ushort v52, v[16:17], off offset:3072
	s_nop 0
	global_load_ushort v16, v[16:17], off offset:3584
	s_nop 0
	global_load_ushort v17, v[20:21], off
	global_load_ushort v53, v[20:21], off offset:512
	global_load_ushort v54, v[22:23], off
	global_load_ushort v55, v[22:23], off offset:512
	global_load_ushort v56, v[20:21], off offset:1024
	global_load_ushort v57, v[20:21], off offset:1536
	global_load_ushort v58, v[20:21], off offset:2048
	global_load_ushort v59, v[20:21], off offset:2560
	global_load_ushort v60, v[20:21], off offset:3072
	s_nop 0
	global_load_ushort v20, v[20:21], off offset:3584
	s_nop 0
	global_load_ushort v21, v[14:15], off offset:-4096
	global_load_ushort v61, v[14:15], off
	global_load_ushort v62, v[22:23], off offset:1024
	global_load_ushort v63, v[22:23], off offset:1536
	global_load_ushort v64, v[22:23], off offset:2048
	global_load_ushort v65, v[22:23], off offset:2560
	global_load_ushort v66, v[22:23], off offset:3072
	s_nop 0
	global_load_ushort v22, v[22:23], off offset:3584
	v_add_co_u32_e32 v12, vcc, 0xb952000, v6
	global_load_dword v23, v[10:11], off
	global_load_dword v67, v[10:11], off offset:1024
	global_load_dword v68, v[10:11], off offset:2048
	global_load_dword v69, v[10:11], off offset:3072
	global_load_dword v70, v[24:25], off
	global_load_dword v71, v[24:25], off offset:1024
	global_load_dword v72, v[24:25], off offset:2048
	s_nop 0
	global_load_dword v24, v[24:25], off offset:3072
	v_addc_co_u32_e32 v13, vcc, 0, v7, vcc
	v_add_co_u32_e32 v10, vcc, 0xb953000, v6
	v_lshl_add_u64 v[0:1], v[0:1], 0, s[54:55]
	s_nop 0
	v_addc_co_u32_e32 v11, vcc, 0, v7, vcc
	v_add_co_u32_e32 v14, vcc, 0xb954000, v6
	global_load_dword v25, v[12:13], off
	global_load_dword v73, v[12:13], off offset:1024
	global_load_dword v74, v[12:13], off offset:2048
	global_load_dword v75, v[12:13], off offset:3072
	global_load_dword v76, v[10:11], off
	global_load_dword v77, v[10:11], off offset:1024
	global_load_dword v78, v[10:11], off offset:2048
	global_load_dword v79, v[10:11], off offset:3072
	v_addc_co_u32_e32 v15, vcc, 0, v7, vcc
	v_add_co_u32_e32 v10, vcc, 0xb955000, v6
	v_lshl_add_u64 v[2:3], v[2:3], 0, s[56:57]
	s_nop 0
	v_addc_co_u32_e32 v11, vcc, 0, v7, vcc
	v_add_co_u32_e32 v12, vcc, 0xb956000, v6
	global_load_dword v80, v[14:15], off
	global_load_dword v81, v[14:15], off offset:1024
	global_load_dword v82, v[14:15], off offset:2048
	s_nop 0
	global_load_dword v14, v[14:15], off offset:3072
	s_nop 0
	global_load_dword v15, v[10:11], off
	global_load_dword v83, v[10:11], off offset:1024
	global_load_dword v84, v[10:11], off offset:2048
	global_load_dword v85, v[10:11], off offset:3072
	v_addc_co_u32_e32 v13, vcc, 0, v7, vcc
	v_add_co_u32_e32 v6, vcc, 0xb957000, v6
	s_cmp_eq_u32 s39, 0
	s_nop 0
	v_addc_co_u32_e32 v7, vcc, 0, v7, vcc
	v_add_co_u32_e32 v10, vcc, 0x9850000, v4
	global_load_dword v86, v[12:13], off
	global_load_dword v87, v[12:13], off offset:1024
	global_load_dword v88, v[12:13], off offset:2048
	s_nop 0
	global_load_dword v12, v[12:13], off offset:3072
	s_nop 0
	global_load_dword v13, v[6:7], off
	global_load_dword v89, v[6:7], off offset:1024
	global_load_dword v90, v[6:7], off offset:2048
	s_nop 0
	global_load_dword v6, v[6:7], off offset:3072
	v_addc_co_u32_e32 v11, vcc, 0, v5, vcc
	v_add_co_u32_e32 v4, vcc, 0xa090000, v4
	s_waitcnt vmcnt(62)
; #define LAS __attribute__((address_space(3)))
; DI bf16_t f2bf(float a) { return (bf16_t)(pk2(a, 0.f) & 0xffffu); }
; DI float bf2f(bf16_t v) { return __uint_as_float(((unsigned)v) << 16); }
; template <bool SAMPLE>
; DI void gla_out(const Params& p, int item, int tbsel, LAS unsigned char* wl, int lane) {
;     ...
; #pragma unroll
;         for (int t = 0; t < HB; ++t) {
;             cum += lav[t];
;             const float qv = bf2f(qvv[t]) * __expf(cum), kv = bf2f(kvv[t]) * __expf(-cum);
;             *(LAS bf16_t*)(Qs + (hf * 32 + t) * 144 + 2 * lane) = f2bf(qv);
;             *(LAS bf16_t*)(Ks + (hf * 32 + t) * 144 + 2 * lane) = f2bf(kv);
;         }
	v_lshlrev_b32_e32 v26, 16, v26
	v_addc_co_u32_e32 v5, vcc, 0, v5, vcc
	global_load_ushort v7, v[10:11], off
	global_load_ushort v91, v[10:11], off offset:512
	global_load_ushort v92, v[10:11], off offset:1024
	global_load_ushort v93, v[10:11], off offset:1536
	global_load_ushort v94, v[10:11], off offset:2048
	global_load_ushort v95, v[10:11], off offset:2560
	global_load_ushort v96, v[10:11], off offset:3072
	s_nop 0
	global_load_ushort v10, v[10:11], off offset:3584
	s_nop 0
	global_load_ushort v11, v[4:5], off
	global_load_ushort v97, v[4:5], off offset:512
	global_load_ushort v98, v[4:5], off offset:1024
	global_load_ushort v99, v[4:5], off offset:1536
	global_load_ushort v100, v[4:5], off offset:2048
	global_load_ushort v101, v[4:5], off offset:2560
	global_load_ushort v102, v[4:5], off offset:3072
	s_nop 0
	global_load_ushort v4, v[4:5], off offset:3584
	v_lshlrev_b32_e32 v27, 16, v27
	v_lshlrev_b32_e32 v28, 16, v28
	v_lshlrev_b32_e32 v29, 16, v29
	v_lshlrev_b32_e32 v30, 16, v30
	v_lshlrev_b32_e32 v31, 16, v31
	v_lshlrev_b32_e32 v32, 16, v32
	v_lshlrev_b32_e32 v33, 16, v33
	v_lshlrev_b32_e32 v42, 16, v42
	v_lshlrev_b32_e32 v35, 16, v35
	v_lshlrev_b32_e32 v43, 16, v43
	v_lshlrev_b32_e32 v36, 16, v36
	s_waitcnt vmcnt(62)
	v_lshlrev_b32_e32 v44, 16, v44
	v_lshlrev_b32_e32 v37, 16, v37
	v_lshlrev_b32_e32 v45, 16, v45
	v_lshlrev_b32_e32 v38, 16, v38
	v_lshlrev_b32_e32 v19, 16, v19
	v_lshlrev_b32_e32 v46, 16, v46
	v_lshlrev_b32_e32 v39, 16, v39
	v_lshlrev_b32_e32 v47, 16, v47
	v_lshlrev_b32_e32 v40, 16, v40
	v_lshlrev_b32_e32 v16, 16, v16
	v_lshlrev_b32_e32 v48, 16, v48
	v_lshlrev_b32_e32 v41, 16, v41
	v_lshlrev_b32_e32 v18, 16, v18
	v_lshlrev_b32_e32 v17, 16, v17
	v_lshlrev_b32_e32 v54, 16, v54
	v_lshlrev_b32_e32 v53, 16, v53
	v_lshlrev_b32_e32 v55, 16, v55
	s_waitcnt vmcnt(61)
	v_lshlrev_b32_e32 v56, 16, v56
	s_waitcnt vmcnt(60)
	v_lshlrev_b32_e32 v57, 16, v57
	s_waitcnt vmcnt(59)
	v_lshlrev_b32_e32 v58, 16, v58
	s_waitcnt vmcnt(55)
	v_lshlrev_b32_e32 v5, 16, v21
	v_lshlrev_b32_e32 v21, 16, v34
	v_lshlrev_b32_e32 v34, 16, v49
	s_waitcnt vmcnt(47)
	v_add_f32_e32 v9, v9, v23
	v_lshlrev_b32_e32 v49, 16, v50
	v_lshlrev_b32_e32 v50, 16, v51
	v_lshlrev_b32_e32 v51, 16, v52
	v_lshlrev_b32_e32 v52, 16, v61
	v_lshlrev_b32_e32 v61, 16, v62
	v_lshlrev_b32_e32 v62, 16, v63
	v_lshlrev_b32_e32 v63, 16, v64
	v_lshlrev_b32_e32 v64, 16, v65
	v_lshlrev_b32_e32 v65, 16, v66
	v_mul_f32_e32 v23, 0x3fb8aa3b, v9
	v_mul_f32_e32 v66, 0xbfb8aa3b, v9
	s_waitcnt vmcnt(46)
	v_add_f32_e32 v9, v9, v67
	v_mul_f32_e32 v67, 0x3fb8aa3b, v9
	v_mul_f32_e32 v103, 0xbfb8aa3b, v9
	s_waitcnt vmcnt(45)
	v_add_f32_e32 v9, v9, v68
	v_exp_f32_e32 v68, v103
	v_mul_f32_e32 v103, 0x3fb8aa3b, v9
	v_mul_f32_e32 v104, 0xbfb8aa3b, v9
	s_waitcnt vmcnt(44)
	v_add_f32_e32 v9, v9, v69
	v_exp_f32_e32 v69, v103
	v_exp_f32_e32 v103, v104
	v_mul_f32_e32 v104, 0x3fb8aa3b, v9
	v_mul_f32_e32 v105, 0xbfb8aa3b, v9
	s_waitcnt vmcnt(43)
	v_add_f32_e32 v9, v9, v70
	v_exp_f32_e32 v23, v23
	v_exp_f32_e32 v67, v67
	v_exp_f32_e32 v70, v104
	v_exp_f32_e32 v104, v105
	v_mul_f32_e32 v105, 0x3fb8aa3b, v9
	v_mul_f32_e32 v106, 0xbfb8aa3b, v9
	s_waitcnt vmcnt(42)
	v_add_f32_e32 v9, v9, v71
	v_exp_f32_e32 v66, v66
	v_exp_f32_e32 v71, v105
	v_exp_f32_e32 v105, v106
	v_mul_f32_e32 v106, 0x3fb8aa3b, v9
	v_mul_f32_e32 v107, 0xbfb8aa3b, v9
	s_waitcnt vmcnt(41)
	v_add_f32_e32 v9, v9, v72
	v_exp_f32_e32 v72, v106
	v_exp_f32_e32 v106, v107
	v_mul_f32_e32 v107, 0x3fb8aa3b, v9
	v_mul_f32_e32 v108, 0xbfb8aa3b, v9
	s_waitcnt vmcnt(40)
	v_add_f32_e32 v9, v9, v24
	s_waitcnt vmcnt(15)
	v_lshlrev_b32_e32 v7, 16, v7
	s_waitcnt vmcnt(14)
	v_lshlrev_b32_e32 v24, 16, v91
	s_waitcnt vmcnt(13)
	v_lshlrev_b32_e32 v91, 16, v92
	s_waitcnt vmcnt(12)
	v_lshlrev_b32_e32 v92, 16, v93
	s_waitcnt vmcnt(11)
	v_lshlrev_b32_e32 v93, 16, v94
	s_waitcnt vmcnt(10)
	v_lshlrev_b32_e32 v94, 16, v95
	s_waitcnt vmcnt(9)
	v_lshlrev_b32_e32 v95, 16, v96
	v_exp_f32_e32 v96, v107
	v_exp_f32_e32 v107, v108
	v_mul_f32_e32 v108, 0x3fb8aa3b, v9
	v_mul_f32_e32 v109, 0xbfb8aa3b, v9
	v_add_f32_e32 v9, v9, v25
	v_mul_f32_e32 v7, v23, v7
	s_waitcnt vmcnt(7)
	v_lshlrev_b32_e32 v11, 16, v11
	v_mul_f32_e32 v23, v67, v24
	s_waitcnt vmcnt(6)
	v_lshlrev_b32_e32 v24, 16, v97
	v_mul_f32_e32 v25, v69, v91
	s_waitcnt vmcnt(5)
	v_lshlrev_b32_e32 v67, 16, v98
	v_mul_f32_e32 v69, v70, v92
	s_waitcnt vmcnt(4)
	v_lshlrev_b32_e32 v70, 16, v99
	s_waitcnt vmcnt(3)
	v_lshlrev_b32_e32 v91, 16, v100
	s_waitcnt vmcnt(2)
	v_lshlrev_b32_e32 v92, 16, v101
	v_exp_f32_e32 v98, v108
	v_exp_f32_e32 v99, v109
	v_mul_f32_e32 v100, 0x3fb8aa3b, v9
	v_mul_f32_e32 v101, 0xbfb8aa3b, v9
	v_add_f32_e32 v9, v9, v73
	v_mul_f32_e32 v11, v66, v11
	v_cvt_pk_bf16_f32 v7, v7, s0
	v_mul_f32_e32 v24, v68, v24
	v_cvt_pk_bf16_f32 v23, v23, s0
	v_mul_f32_e32 v66, v103, v67
	v_cvt_pk_bf16_f32 v25, v25, s0
	v_mul_f32_e32 v67, v104, v70
	v_cvt_pk_bf16_f32 v68, v69, s0
	v_mul_f32_e32 v69, v71, v93
	v_mul_f32_e32 v70, v105, v91
	v_exp_f32_e32 v71, v100
	v_exp_f32_e32 v73, v101
	v_mul_f32_e32 v91, 0x3fb8aa3b, v9
	v_mul_f32_e32 v93, 0xbfb8aa3b, v9
	v_add_f32_e32 v9, v9, v74
	s_waitcnt vmcnt(1)
	v_lshlrev_b32_e32 v97, 16, v102
	ds_write_b16 v8, v7
	v_cvt_pk_bf16_f32 v7, v11, s0
	ds_write_b16 v8, v23 offset:144
	v_cvt_pk_bf16_f32 v11, v24, s0
	ds_write_b16 v8, v25 offset:288
	v_cvt_pk_bf16_f32 v23, v66, s0
	ds_write_b16 v8, v68 offset:432
	v_cvt_pk_bf16_f32 v24, v67, s0
	v_cvt_pk_bf16_f32 v25, v69, s0
	v_cvt_pk_bf16_f32 v66, v70, s0
	v_mul_f32_e32 v67, v72, v94
	v_mul_f32_e32 v68, v106, v92
	v_exp_f32_e32 v69, v91
	v_exp_f32_e32 v70, v93
	v_mul_f32_e32 v72, 0x3fb8aa3b, v9
	v_mul_f32_e32 v74, 0xbfb8aa3b, v9
	v_add_f32_e32 v9, v9, v75
	v_lshlrev_b32_e32 v10, 16, v10
	s_waitcnt vmcnt(0)
; #define LAS __attribute__((address_space(3)))
; DI bf16_t f2bf(float a) { return (bf16_t)(pk2(a, 0.f) & 0xffffu); }
; DI float bf2f(bf16_t v) { return __uint_as_float(((unsigned)v) << 16); }
; template <bool SAMPLE>
; DI void gla_out(const Params& p, int item, int tbsel, LAS unsigned char* wl, int lane) {
;     ...
;         for (int t = 0; t < HB; ++t) {
;             cum += lav[t];
;             const float qv = bf2f(qvv[t]) * __expf(cum), kv = bf2f(kvv[t]) * __expf(-cum);
;             *(LAS bf16_t*)(Qs + (hf * 32 + t) * 144 + 2 * lane) = f2bf(qv);
;             *(LAS bf16_t*)(Ks + (hf * 32 + t) * 144 + 2 * lane) = f2bf(kv);
;         }
	v_lshlrev_b32_e32 v4, 16, v4
	ds_write_b16 v8, v7 offset:9216
	ds_write_b16 v8, v11 offset:9360
	ds_write_b16 v8, v23 offset:9504
	ds_write_b16 v8, v24 offset:9648
	ds_write_b16 v8, v25 offset:576
	ds_write_b16 v8, v66 offset:9792
	v_cvt_pk_bf16_f32 v7, v67, s0
	v_cvt_pk_bf16_f32 v11, v68, s0
	v_mul_f32_e32 v23, v96, v95
	v_mul_f32_e32 v24, v107, v97
	v_exp_f32_e32 v25, v72
	v_exp_f32_e32 v66, v74
	v_mul_f32_e32 v67, 0x3fb8aa3b, v9
	v_mul_f32_e32 v68, 0xbfb8aa3b, v9
	v_add_f32_e32 v9, v9, v76
	ds_write_b16 v8, v7 offset:720
	ds_write_b16 v8, v11 offset:9936
	v_cvt_pk_bf16_f32 v7, v23, s0
	v_cvt_pk_bf16_f32 v11, v24, s0
	v_mul_f32_e32 v10, v98, v10
	v_mul_f32_e32 v4, v99, v4
	v_exp_f32_e32 v23, v67
	v_exp_f32_e32 v24, v68
	v_mul_f32_e32 v67, 0x3fb8aa3b, v9
	v_mul_f32_e32 v68, 0xbfb8aa3b, v9
	v_add_f32_e32 v9, v9, v77
	ds_write_b16 v8, v7 offset:864
	ds_write_b16 v8, v11 offset:10080
	v_cvt_pk_bf16_f32 v7, v10, s0
	v_cvt_pk_bf16_f32 v4, v4, s0
	v_mul_f32_e32 v5, v71, v5
	v_mul_f32_e32 v10, v73, v21
	v_exp_f32_e32 v11, v67
	v_exp_f32_e32 v21, v68
	v_mul_f32_e32 v67, 0x3fb8aa3b, v9
	v_mul_f32_e32 v68, 0xbfb8aa3b, v9
	v_add_f32_e32 v9, v9, v78
	ds_write_b16 v8, v7 offset:1008
	ds_write_b16 v8, v4 offset:10224
	v_cvt_pk_bf16_f32 v4, v5, s0
	v_cvt_pk_bf16_f32 v5, v10, s0
	v_mul_f32_e32 v7, v69, v26
	v_mul_f32_e32 v10, v70, v27
	v_exp_f32_e32 v26, v67
	v_exp_f32_e32 v27, v68
	v_mul_f32_e32 v67, 0x3fb8aa3b, v9
	v_mul_f32_e32 v68, 0xbfb8aa3b, v9
	v_add_f32_e32 v9, v9, v79
	ds_write_b16 v8, v4 offset:1152
	ds_write_b16 v8, v5 offset:10368
	v_cvt_pk_bf16_f32 v4, v7, s0
	v_cvt_pk_bf16_f32 v5, v10, s0
	v_mul_f32_e32 v7, v25, v28
	v_mul_f32_e32 v10, v66, v19
	v_exp_f32_e32 v19, v67
	v_exp_f32_e32 v25, v68
	v_mul_f32_e32 v28, 0x3fb8aa3b, v9
	v_mul_f32_e32 v66, 0xbfb8aa3b, v9
	v_add_f32_e32 v9, v9, v80
	ds_write_b16 v8, v4 offset:1296
	ds_write_b16 v8, v5 offset:10512
	v_cvt_pk_bf16_f32 v4, v7, s0
	v_cvt_pk_bf16_f32 v5, v10, s0
	v_mul_f32_e32 v7, v23, v29
	v_mul_f32_e32 v10, v24, v34
	v_exp_f32_e32 v23, v28
	v_exp_f32_e32 v24, v66
	v_mul_f32_e32 v28, 0x3fb8aa3b, v9
	v_mul_f32_e32 v29, 0xbfb8aa3b, v9
	v_add_f32_e32 v9, v9, v81
	ds_write_b16 v8, v4 offset:1440
	ds_write_b16 v8, v5 offset:10656
	v_cvt_pk_bf16_f32 v4, v7, s0
	v_cvt_pk_bf16_f32 v5, v10, s0
	v_mul_f32_e32 v7, v11, v30
	v_mul_f32_e32 v10, v21, v49
	v_exp_f32_e32 v11, v28
	v_exp_f32_e32 v21, v29
	v_mul_f32_e32 v28, 0x3fb8aa3b, v9
	v_mul_f32_e32 v29, 0xbfb8aa3b, v9
	v_add_f32_e32 v9, v9, v82
	ds_write_b16 v8, v4 offset:1584
	ds_write_b16 v8, v5 offset:10800
	v_cvt_pk_bf16_f32 v4, v7, s0
	v_cvt_pk_bf16_f32 v5, v10, s0
	v_mul_f32_e32 v7, v26, v31
	v_mul_f32_e32 v10, v27, v50
	v_exp_f32_e32 v26, v28
	v_exp_f32_e32 v27, v29
	v_mul_f32_e32 v28, 0x3fb8aa3b, v9
	v_mul_f32_e32 v29, 0xbfb8aa3b, v9
	v_add_f32_e32 v9, v9, v14
	ds_write_b16 v8, v4 offset:1728
	ds_write_b16 v8, v5 offset:10944
	v_cvt_pk_bf16_f32 v4, v7, s0
	v_cvt_pk_bf16_f32 v5, v10, s0
	v_mul_f32_e32 v7, v19, v32
	v_mul_f32_e32 v10, v25, v51
	v_exp_f32_e32 v14, v28
	v_exp_f32_e32 v19, v29
	v_mul_f32_e32 v25, 0x3fb8aa3b, v9
	v_mul_f32_e32 v28, 0xbfb8aa3b, v9
	v_add_f32_e32 v9, v9, v15
	ds_write_b16 v8, v4 offset:1872
	ds_write_b16 v8, v5 offset:11088
	v_cvt_pk_bf16_f32 v4, v7, s0
	v_cvt_pk_bf16_f32 v5, v10, s0
	v_mul_f32_e32 v7, v23, v33
	v_mul_f32_e32 v10, v24, v16
	v_exp_f32_e32 v15, v25
	v_exp_f32_e32 v16, v28
	v_mul_f32_e32 v23, 0x3fb8aa3b, v9
	v_mul_f32_e32 v24, 0xbfb8aa3b, v9
	v_add_f32_e32 v9, v9, v83
	ds_write_b16 v8, v4 offset:2016
	ds_write_b16 v8, v5 offset:11232
	v_cvt_pk_bf16_f32 v4, v7, s0
	v_cvt_pk_bf16_f32 v5, v10, s0
	v_mul_f32_e32 v7, v11, v52
	v_mul_f32_e32 v10, v21, v42
	v_exp_f32_e32 v11, v23
	v_exp_f32_e32 v21, v24
	v_mul_f32_e32 v23, 0x3fb8aa3b, v9
	v_mul_f32_e32 v24, 0xbfb8aa3b, v9
	v_add_f32_e32 v9, v9, v84
	ds_write_b16 v8, v4 offset:2160
	ds_write_b16 v8, v5 offset:11376
	v_cvt_pk_bf16_f32 v4, v7, s0
	v_cvt_pk_bf16_f32 v5, v10, s0
	v_mul_f32_e32 v7, v26, v35
	v_mul_f32_e32 v10, v27, v43
	v_exp_f32_e32 v23, v23
	v_exp_f32_e32 v24, v24
	v_mul_f32_e32 v25, 0x3fb8aa3b, v9
	v_mul_f32_e32 v26, 0xbfb8aa3b, v9
	v_add_f32_e32 v9, v9, v85
	ds_write_b16 v8, v4 offset:2304
	ds_write_b16 v8, v5 offset:11520
	v_cvt_pk_bf16_f32 v4, v7, s0
	v_cvt_pk_bf16_f32 v5, v10, s0
	v_mul_f32_e32 v7, v14, v36
	v_mul_f32_e32 v10, v19, v44
	v_exp_f32_e32 v14, v25
	v_exp_f32_e32 v19, v26
	v_mul_f32_e32 v25, 0x3fb8aa3b, v9
	v_mul_f32_e32 v26, 0xbfb8aa3b, v9
	v_add_f32_e32 v9, v9, v86
	ds_write_b16 v8, v4 offset:2448
	ds_write_b16 v8, v5 offset:11664
	v_cvt_pk_bf16_f32 v4, v7, s0
; #define LAS __attribute__((address_space(3)))
; DI bf16_t f2bf(float a) { return (bf16_t)(pk2(a, 0.f) & 0xffffu); }
; DI float bf2f(bf16_t v) { return __uint_as_float(((unsigned)v) << 16); }
; DI unsigned xb_ld(unsigned* p)              { return __hip_atomic_load(p, __ATOMIC_RELAXED, __HIP_MEMORY_SCOPE_AGENT); }
; #define XB_SPIN(cond, bar) do { unsigned _sp = 0; while (cond) { __builtin_amdgcn_s_sleep(1); \
;     if ((++_sp & 255u) == 0u) { if (xb_ld(&(bar)[XB_TMO])) break; if (_sp > XB_SPIN_CAP) { atomicAdd(&(bar)[XB_TMO], 1u); break; } } } } while (0)
; template <bool SAMPLE>
; DI void gla_out(const Params& p, int item, int tbsel, LAS unsigned char* wl, int lane) {
;     ...
;         for (int t = 0; t < HB; ++t) {
;             cum += lav[t];
;             const float qv = bf2f(qvv[t]) * __expf(cum), kv = bf2f(kvv[t]) * __expf(-cum);
;             *(LAS bf16_t*)(Qs + (hf * 32 + t) * 144 + 2 * lane) = f2bf(qv);
;             *(LAS bf16_t*)(Ks + (hf * 32 + t) * 144 + 2 * lane) = f2bf(kv);
;         }
;     }
; DI void xcd_barrier(const XcdBarrier& b) {
;     ...
;         } else {
;             XB_SPIN(xb_ld(&bar[XB_XGEN(b.x)]) == gen, bar);
	v_cvt_pk_bf16_f32 v5, v10, s0
	v_mul_f32_e32 v7, v15, v37
	v_mul_f32_e32 v10, v16, v45
	v_exp_f32_e32 v15, v25
	v_exp_f32_e32 v16, v26
	v_mul_f32_e32 v25, 0x3fb8aa3b, v9
	v_mul_f32_e32 v26, 0xbfb8aa3b, v9
	v_add_f32_e32 v9, v9, v87
	ds_write_b16 v8, v4 offset:2592
	ds_write_b16 v8, v5 offset:11808
	v_cvt_pk_bf16_f32 v4, v7, s0
	v_cvt_pk_bf16_f32 v5, v10, s0
	v_mul_f32_e32 v7, v11, v38
	v_mul_f32_e32 v10, v21, v46
	v_exp_f32_e32 v11, v25
	v_exp_f32_e32 v21, v26
	v_mul_f32_e32 v25, 0x3fb8aa3b, v9
	v_mul_f32_e32 v26, 0xbfb8aa3b, v9
	v_add_f32_e32 v9, v9, v88
	ds_write_b16 v8, v4 offset:2736
	ds_write_b16 v8, v5 offset:11952
	v_cvt_pk_bf16_f32 v4, v7, s0
	v_cvt_pk_bf16_f32 v5, v10, s0
	v_mul_f32_e32 v7, v23, v39
	v_mul_f32_e32 v10, v24, v47
	v_exp_f32_e32 v23, v25
	v_exp_f32_e32 v24, v26
	v_mul_f32_e32 v25, 0x3fb8aa3b, v9
	v_mul_f32_e32 v26, 0xbfb8aa3b, v9
	v_add_f32_e32 v9, v9, v12
	ds_write_b16 v8, v4 offset:2880
	ds_write_b16 v8, v5 offset:12096
	v_cvt_pk_bf16_f32 v4, v7, s0
	v_cvt_pk_bf16_f32 v5, v10, s0
	v_mul_f32_e32 v7, v14, v40
	v_mul_f32_e32 v10, v19, v48
	v_exp_f32_e32 v12, v25
	v_exp_f32_e32 v14, v26
	v_mul_f32_e32 v19, 0x3fb8aa3b, v9
	v_mul_f32_e32 v25, 0xbfb8aa3b, v9
	v_add_f32_e32 v9, v9, v13
	ds_write_b16 v8, v4 offset:3024
	ds_write_b16 v8, v5 offset:12240
	v_cvt_pk_bf16_f32 v4, v7, s0
	v_cvt_pk_bf16_f32 v5, v10, s0
	v_mul_f32_e32 v7, v15, v41
	v_mul_f32_e32 v10, v16, v18
	v_exp_f32_e32 v13, v19
	v_mul_f32_e32 v16, 0x3fb8aa3b, v9
	v_mul_f32_e32 v18, 0xbfb8aa3b, v9
	v_add_f32_e32 v9, v9, v89
	v_exp_f32_e32 v15, v25
	ds_write_b16 v8, v4 offset:3168
	ds_write_b16 v8, v5 offset:12384
	v_cvt_pk_bf16_f32 v4, v7, s0
	v_cvt_pk_bf16_f32 v5, v10, s0
	v_mul_f32_e32 v7, v11, v17
	v_mul_f32_e32 v10, v21, v54
	v_exp_f32_e32 v11, v16
	v_exp_f32_e32 v16, v18
	v_mul_f32_e32 v17, 0x3fb8aa3b, v9
	v_mul_f32_e32 v18, 0xbfb8aa3b, v9
	v_add_f32_e32 v9, v9, v90
	ds_write_b16 v8, v4 offset:3312
	ds_write_b16 v8, v5 offset:12528
	v_cvt_pk_bf16_f32 v4, v7, s0
	v_cvt_pk_bf16_f32 v5, v10, s0
	v_mul_f32_e32 v7, v23, v53
	v_mul_f32_e32 v10, v24, v55
	v_exp_f32_e32 v17, v17
	v_mul_f32_e32 v19, 0x3fb8aa3b, v9
	v_mul_f32_e32 v21, 0xbfb8aa3b, v9
	v_add_f32_e32 v9, v9, v6
	v_exp_f32_e32 v18, v18
	ds_write_b16 v8, v4 offset:3456
	ds_write_b16 v8, v5 offset:12672
	v_cvt_pk_bf16_f32 v4, v7, s0
	v_cvt_pk_bf16_f32 v5, v10, s0
	v_mul_f32_e32 v6, v12, v56
	v_mul_f32_e32 v7, v14, v61
	v_exp_f32_e32 v10, v19
	v_mul_f32_e32 v14, 0x3fb8aa3b, v9
	v_exp_f32_e32 v12, v21
	v_mul_f32_e32 v19, 0xbfb8aa3b, v9
	ds_write_b16 v8, v4 offset:3600
	ds_write_b16 v8, v5 offset:12816
	v_cvt_pk_bf16_f32 v4, v6, s0
	v_mul_f32_e32 v6, v13, v57
	v_exp_f32_e32 v13, v14
	v_lshlrev_b32_e32 v59, 16, v59
	v_cvt_pk_bf16_f32 v5, v7, s0
	v_mul_f32_e32 v7, v15, v62
	v_exp_f32_e32 v14, v19
	ds_write_b16 v8, v4 offset:3744
	ds_write_b16 v8, v5 offset:12960
	v_cvt_pk_bf16_f32 v4, v6, s0
	v_mul_f32_e32 v6, v11, v58
	v_lshlrev_b32_e32 v60, 16, v60
	v_cvt_pk_bf16_f32 v5, v7, s0
	v_mul_f32_e32 v7, v16, v63
	ds_write_b16 v8, v4 offset:3888
	ds_write_b16 v8, v5 offset:13104
	v_cvt_pk_bf16_f32 v4, v6, s0
	v_mul_f32_e32 v6, v17, v59
	v_lshlrev_b32_e32 v20, 16, v20
	v_cvt_pk_bf16_f32 v5, v7, s0
	v_mul_f32_e32 v7, v18, v64
	ds_write_b16 v8, v4 offset:4032
	ds_write_b16 v8, v5 offset:13248
	v_cvt_pk_bf16_f32 v4, v6, s0
	v_mul_f32_e32 v6, v10, v60
	v_lshlrev_b32_e32 v22, 16, v22
	v_cvt_pk_bf16_f32 v5, v7, s0
	v_mul_f32_e32 v7, v12, v65
	ds_write_b16 v8, v4 offset:4176
	ds_write_b16 v8, v5 offset:13392
	v_cvt_pk_bf16_f32 v4, v6, s0
	v_mul_f32_e32 v6, v13, v20
	v_cvt_pk_bf16_f32 v5, v7, s0
	v_mul_f32_e32 v7, v14, v22
	ds_write_b16 v8, v4 offset:4320
	ds_write_b16 v8, v5 offset:13536
	v_cvt_pk_bf16_f32 v4, v6, s0
	v_cvt_pk_bf16_f32 v5, v7, s0
	ds_write_b16 v8, v4 offset:4464
	ds_write_b16 v8, v5 offset:13680
	v_add_u32_e32 v8, 0x1200, v8
	s_cbranch_scc0 .LBB0_1132
	s_cmp_eq_u32 s100, 0
	s_cbranch_scc1 .Lsb4_done
	s_mov_b32 s100, 0
	v_cmp_eq_u32_e32 vcc, 0, v203
	s_and_saveexec_b64 s[40:41], vcc
	s_cbranch_execz .Lsb4_join
	s_lshl_b32 s76, s33, 8
	s_add_u32 s76, s46, s76
	s_addc_u32 s77, s47, 0
	s_mov_b32 s78, 0
	s_cmp_eq_u32 s101, 2
	s_cbranch_scc1 .Lsb4_lead_go
	s_cmp_eq_u32 s101, 1
	s_cbranch_scc1 .Lsb4_lead_wait
	v_mov_b32_e32 v160, 0x3100
.Lsb4_nl:
	global_load_dword v161, v160, s[46:47] offset:1024 sc1
	s_waitcnt vmcnt(0)
	v_readfirstlane_b32 s79, v161
	s_cmp_lg_u32 s79, 3
	s_cbranch_scc1 .Lsb4_acq
	s_add_i32 s78, s78, 1
	s_cmp_lt_u32 s78, 0x800
	s_cbranch_scc0 .Lsb4_acq
	s_sleep 1
	s_branch .Lsb4_nl
.Lsb4_lead_wait:
	v_mov_b32_e32 v160, 0x3100

; DI unsigned xb_ld(unsigned* p)              { return __hip_atomic_load(p, __ATOMIC_RELAXED, __HIP_MEMORY_SCOPE_AGENT); }
; #define XB_SPIN(cond, bar) do { unsigned _sp = 0; while (cond) { __builtin_amdgcn_s_sleep(1); \
;     if ((++_sp & 255u) == 0u) { if (xb_ld(&(bar)[XB_TMO])) break; if (_sp > XB_SPIN_CAP) { atomicAdd(&(bar)[XB_TMO], 1u); break; } } } } while (0)
; DI void xcd_barrier(const XcdBarrier& b) {
;     ...
;         } else {
;             XB_SPIN(xb_ld(&bar[XB_XGEN(b.x)]) == gen, bar);
.LBB0_1139:
	s_cmp_eq_u32 s100, 0
	s_cbranch_scc1 .Lsb4b_done
	s_mov_b32 s100, 0
	v_cmp_eq_u32_e32 vcc, 0, v203
	s_and_saveexec_b64 s[40:41], vcc
	s_cbranch_execz .Lsb4b_join
	s_lshl_b32 s76, s33, 8
	s_add_u32 s76, s46, s76
	s_addc_u32 s77, s47, 0
	s_mov_b32 s78, 0
	s_cmp_eq_u32 s101, 2
	s_cbranch_scc1 .Lsb4b_lead_go
	s_cmp_eq_u32 s101, 1
	s_cbranch_scc1 .Lsb4b_lead_wait
	v_mov_b32_e32 v160, 0x3100
.Lsb4b_nl:
	global_load_dword v161, v160, s[46:47] offset:1024 sc1
	s_waitcnt vmcnt(0)
	v_readfirstlane_b32 s79, v161
	s_cmp_lg_u32 s79, 3
	s_cbranch_scc1 .Lsb4b_acq
	s_add_i32 s78, s78, 1
	s_cmp_lt_u32 s78, 0x800
	s_cbranch_scc0 .Lsb4b_acq
	s_sleep 1
	s_branch .Lsb4b_nl
.Lsb4b_lead_wait:
	v_mov_b32_e32 v160, 0x3100

; DI unsigned xb_ld(unsigned* p)              { return __hip_atomic_load(p, __ATOMIC_RELAXED, __HIP_MEMORY_SCOPE_AGENT); }
; #define XB_SPIN(cond, bar) do { unsigned _sp = 0; while (cond) { __builtin_amdgcn_s_sleep(1); \
;     if ((++_sp & 255u) == 0u) { if (xb_ld(&(bar)[XB_TMO])) break; if (_sp > XB_SPIN_CAP) { atomicAdd(&(bar)[XB_TMO], 1u); break; } } } } while (0)
; DI void xcd_barrier(const XcdBarrier& b) {
;     ...
;         } else {
;             XB_SPIN(xb_ld(&bar[XB_XGEN(b.x)]) == gen, bar);
.LBB0_1230:
	s_cmp_eq_u32 s100, 0
	s_cbranch_scc1 .Lsb_done
	s_mov_b32 s100, 0
	v_cmp_eq_u32_e32 vcc, 0, v203
	s_and_saveexec_b64 s[40:41], vcc
	s_cbranch_execz .Lsb_join
	s_lshl_b32 s76, s33, 8
	s_add_u32 s76, s46, s76
	s_addc_u32 s77, s47, 0
	s_mov_b32 s42, 0
	s_cmp_eq_u32 s101, 2
	s_cbranch_scc1 .Lsb_lead_go
	s_cmp_eq_u32 s101, 1
	s_cbranch_scc1 .Lsb_lead_wait
	v_mov_b32_e32 v160, 0x3100
.Lsb_nl:
	global_load_dword v161, v160, s[46:47] offset:1024 sc1
	s_waitcnt vmcnt(0)
	v_readfirstlane_b32 s43, v161
	s_cmp_lg_u32 s43, 4
	s_cbranch_scc1 .Lsb_acq
	s_add_i32 s42, s42, 1
	s_cmp_lt_u32 s42, 0x800
	s_cbranch_scc0 .Lsb_acq
	s_sleep 1
	s_branch .Lsb_nl
.Lsb_lead_wait:
	v_mov_b32_e32 v160, 0x3100
